# combo4 + attention: k_norm loads hoisted out of the K/V loop, K/V row loads prefetched one iteration ahead
# baseline (speedup 1.0000x reference)
; #define LAS __attribute__((address_space(3)))
; __device__ __forceinline__ void attn_items(const Params& p, LAS unsigned char* lds, int ai0, int aistride) {
;     const int tid = threadIdx.x, lane = tid & 63, wid = tid >> 6, fr = lane & 15, fq = lane >> 4;
;     LAS bf16_t* K_s = (LAS bf16_t*)lds;
;     LAS bf16_t* Vt_s = (LAS bf16_t*)(lds + 27648);
;     const bf16_t* Z = (const bf16_t*)(p.ws + WS_Z);
;     bf16_t* CAT = (bf16_t*)(p.ws + WS_CAT);
;     ...
;                 const float4 n0 = *(const float4*)(p.in[10] + d0), n1 = *(const float4*)(p.in[10] + d0 + 4);
.LBB0_514:
.LBB0_515:
	s_add_u32 s14, s50, 0x3000000
	s_addc_u32 s15, s51, 0
	s_add_u32 s16, s50, 0x9b40000
	s_addc_u32 s17, s51, 0
	s_add_u32 s18, s48, 0x459c000
	s_addc_u32 s19, s49, 0
	v_bfe_u32 v1, v184, 4, 2
	s_add_u32 s20, s48, 0x45dc000
	v_lshlrev_b32_e32 v0, 3, v1
	v_lshl_add_u32 v2, v1, 4, 0
	v_lshlrev_b32_e32 v18, 2, v1
	s_addc_u32 s21, s49, 0
	v_lshlrev_b32_e32 v16, 5, v1
	v_and_b32_e32 v1, 0xffffff80, v184
	v_lshrrev_b32_e32 v44, 3, v184
	s_movk_i32 s0, 0x90
	s_add_u32 s22, s48, 0x4200000
	v_sub_u32_e32 v51, 0x400, v1
	v_lshl_add_u32 v1, v44, 1, 0
	v_mul_u32_u24_e32 v4, 0x190, v53
	s_addc_u32 s23, s49, 0
	v_add_u32_e32 v54, 0x6c00, v1
	v_mul_lo_u32 v1, v44, s0
	v_lshrrev_b32_e32 v19, 5, v184
	v_mov_b32_e32 v17, 0
	v_mul_u32_u24_e32 v3, 0x90, v53
	v_add3_u32 v50, 0, v4, v0
	s_add_u32 s24, s48, 0x4280000
	v_add_u32_e32 v55, 0, v1
	v_and_b32_e32 v1, 7, v184
	v_lshlrev_b32_e32 v22, 1, v0
	v_mbcnt_lo_u32_b32 v0, -1, 0
	v_and_b32_e32 v45, 30, v19
	v_not_b32_e32 v46, v18
	v_or_b32_e32 v47, 16, v18
	v_or_b32_e32 v48, 32, v18
	v_or_b32_e32 v49, 48, v18
	s_movk_i32 s34, 0x190
	s_addc_u32 s25, s49, 0
	v_lshl_add_u64 v[20:21], s[70:71], 0, v[16:17]
	s_movk_i32 s35, 0x400
	v_lshlrev_b32_e32 v52, 3, v184
	v_and_b32_e32 v242, 56, v52
	v_lshlrev_b32_e32 v242, 2, v242
	global_load_dwordx4 v[224:227], v242, s[72:73]
	global_load_dwordx4 v[228:231], v242, s[72:73] offset:16
	v_lshlrev_b32_e32 v56, 4, v1
	s_movk_i32 s68, 0x1a00
	v_mov_b32_e32 v57, 0x358637bd
	s_mov_b32 s69, 0x800000
	s_mov_b32 s70, 0x42fc0000
	v_mbcnt_hi_u32_b32 v58, -1, v0
	v_mov_b32_e32 v59, 0x42800000
	v_not_b32_e32 v60, 63
	v_add_u32_e32 v61, v2, v3
	v_mov_b32_e32 v62, 0xf149f2ca
	s_mov_b32 s71, s30
	s_branch .LBB0_517

; __device__ __forceinline__ void attn_items(const Params& p, LAS unsigned char* lds, int ai0, int aistride) {
;     ...
;     for (int ai = ai0; ai < 576; ai += aistride) {
;         const bool samp = ai >= 512;
;         int b, c, g, nkeys, ntt, row0, krow0, nkc;
;         if (!samp) { g = ai & 1; c = (ai >> 1) & 31; b = ai >> 6; nkc = (c < 2 ? c : 2) + 1; nkeys = 64 * nkc; ntt = 4; row0 = b * 2048 + c * 64; krow0 = row0 - (nkc - 1) * 64; }
;         else { const int s = ai - 512; g = s & 1; b = s >> 1; c = 0; nkc = 0; nkeys = 160; ntt = 1; row0 = MP + b * 16; krow0 = 0; }
;         for (int q = tid; q < nkeys * 8; q += 512) {
;             const int key = q >> 3, d0 = (q & 7) * 8;
;             float kf[8], vf[8]; bool donorm = false;
;             if (!samp || (key >= 128 && key < 144)) {
;                 const int row = samp ? row0 + key - 128 : krow0 + key;
;                 const bf16x8 kr = *(const bf16x8*)(Z + (size_t)row * NZ + ZC_AK + g * 64 + d0), vr = *(const bf16x8*)(Z + (size_t)row * NZ + ZC_AV + g * 64 + d0);
.LBB0_522:
	s_lshl_b32 s46, s60, 3
	s_and_b32 s43, s71, 1
	v_cmp_gt_u32_e32 vcc, s46, v184
	s_and_saveexec_b64 s[8:9], vcc
	s_cbranch_execz .LBB0_543
	s_lshl_b32 s47, s4, 7
	s_lshl_b32 s61, s43, 6
	s_add_i32 s26, s40, 0xffffff80
	s_lshl_b32 s27, s4, 4
	s_cmp_lt_u32 s1, 30
	s_cselect_b64 s[4:5], -1, 0
	s_sub_i32 s62, s60, 64
	s_lshl_b32 s1, s1, 6
	s_and_b64 s[10:11], s[2:3], exec
	s_cselect_b32 s63, s0, s26
	s_lshl_b32 s0, s43, 7
	s_add_u32 s10, s14, s0
	s_addc_u32 s11, s15, 0
	s_add_i32 s0, s47, s1
	s_sub_i32 s0, s0, s60
	s_add_i32 s66, s0, 0xfffff8c0
	s_add_i32 s67, s27, 0xffffff80
	s_mov_b32 s76, 0
	s_mov_b64 s[26:27], 0
	s_xor_b64 s[28:29], s[4:5], -1
	v_mov_b32_e32 v23, v55
	v_mov_b32_e32 v28, v54
	v_mov_b32_e32 v29, v52
	v_mov_b32_e32 v30, v51
	v_mov_b32_e32 v31, v184
	v_add_u32_e32 v36, s63, v44
	v_mov_b64_e32 v[34:35], s[10:11]
	v_and_b32_e32 v37, 56, v52
	s_nop 0
	v_mad_i64_i32 v[34:35], vcc, v36, s68, v[34:35]
	v_lshlrev_b32_e32 v36, 1, v37
	v_mov_b32_e32 v37, 0
	v_lshl_add_u64 v[34:35], v[34:35], 0, v[36:37]
	global_load_dwordx4 v[240:243], v[34:35], off offset:1024
	global_load_dwordx4 v[244:247], v[34:35], off offset:1280
	s_branch .LBB0_525

; __device__ __forceinline__ float bf2f(short b) { return __uint_as_float(((unsigned)(unsigned short)b) << 16); }
; __device__ __forceinline__ float sum8(float v) { v += dpp_f<0xB1>(v); v += dpp_f<0x4E>(v); v += dpp_f<0x141>(v); return v; }
; __device__ __forceinline__ void attn_items(const Params& p, LAS unsigned char* lds, int ai0, int aistride) {
;     ...
;             if (!samp || (key >= 128 && key < 144)) {
;                 const int row = samp ? row0 + key - 128 : krow0 + key;
;                 const bf16x8 kr = *(const bf16x8*)(Z + (size_t)row * NZ + ZC_AK + g * 64 + d0), vr = *(const bf16x8*)(Z + (size_t)row * NZ + ZC_AV + g * 64 + d0);
; #pragma unroll
;                 for (int e = 0; e < 8; ++e) { kf[e] = bf2f(kr[e]); vf[e] = bf2f(vr[e]); }
;                 donorm = true;
;             } else if (key < 128) {
;                 const size_t o = ((size_t)(b * 128 + key) * 2 + g) * 64 + d0;
;                 const float4 k0 = *(const float4*)(p.in[2] + o), k1 = *(const float4*)(p.in[2] + o + 4), v0 = *(const float4*)(p.in[3] + o), v1 = *(const float4*)(p.in[3] + o + 4);
;                 kf[0] = k0.x; kf[1] = k0.y; kf[2] = k0.z; kf[3] = k0.w; kf[4] = k1.x; kf[5] = k1.y; kf[6] = k1.z; kf[7] = k1.w;
;                 vf[0] = v0.x; vf[1] = v0.y; vf[2] = v0.z; vf[3] = v0.w; vf[4] = v1.x; vf[5] = v1.y; vf[6] = v1.z; vf[7] = v1.w;
;             } else {
; #pragma unroll
;                 for (int e = 0; e < 8; ++e) { kf[e] = 0.f; vf[e] = 0.f; }
;             }
;             float ss = 0.f;
; #pragma unroll
;             for (int e = 0; e < 8; ++e) ss += kf[e] * kf[e];
;             ss = sum8(ss);
;             if (donorm) { const float r = rsqrtf(ss * (1.0f / 64.0f) + 1e-6f);
;                 const float4 n0 = *(const float4*)(p.in[10] + d0), n1 = *(const float4*)(p.in[10] + d0 + 4);
;                 kf[0] *= r * n0.x; kf[1] *= r * n0.y; kf[2] *= r * n0.z; kf[3] *= r * n0.w; kf[4] *= r * n1.x; kf[5] *= r * n1.y; kf[6] *= r * n1.z; kf[7] *= r * n1.w; }
.LBB0_529:
	s_andn2_saveexec_b64 s[38:39], s[38:39]
	s_cbranch_execz .LBB0_531
	s_waitcnt vmcnt(0)
	v_and_b32_e32 v5, 0xffff0000, v240
	v_and_b32_e32 v7, 0xffff0000, v241
	v_and_b32_e32 v1, 0xffff0000, v242
	v_and_b32_e32 v3, 0xffff0000, v243
	v_lshlrev_b32_e32 v4, 16, v240
	v_lshlrev_b32_e32 v6, 16, v241
	v_lshlrev_b32_e32 v0, 16, v242
	v_lshlrev_b32_e32 v2, 16, v243
	v_and_b32_e32 v13, 0xffff0000, v244
	v_and_b32_e32 v15, 0xffff0000, v245
	v_and_b32_e32 v9, 0xffff0000, v246
	v_and_b32_e32 v11, 0xffff0000, v247
	v_lshlrev_b32_e32 v12, 16, v244
	v_lshlrev_b32_e32 v14, 16, v245
	v_lshlrev_b32_e32 v8, 16, v246
	v_lshlrev_b32_e32 v10, 16, v247
.LBB0_531:
	s_or_b64 exec, exec, s[38:39]
	v_add_u32_e32 v36, s63, v44
	v_mov_b64_e32 v[34:35], s[10:11]
	v_add_u32_e32 v36, 64, v36
	s_nop 0
	v_mad_i64_i32 v[34:35], vcc, v36, s68, v[34:35]
	v_lshlrev_b32_e32 v36, 1, v32
	v_mov_b32_e32 v37, 0
	v_lshl_add_u64 v[34:35], v[34:35], 0, v[36:37]
	global_load_dwordx4 v[240:243], v[34:35], off offset:1024
	global_load_dwordx4 v[244:247], v[34:35], off offset:1280
	s_waitcnt vmcnt(2)
	v_mul_f32_e32 v16, v5, v5
	v_fmac_f32_e32 v16, v4, v4
	v_fmac_f32_e32 v16, v6, v6
	v_fmac_f32_e32 v16, v7, v7
	v_fmac_f32_e32 v16, v0, v0
	v_fmac_f32_e32 v16, v1, v1
	v_fmac_f32_e32 v16, v2, v2
	v_fmac_f32_e32 v16, v3, v3
	s_nop 1
	v_add_f32_dpp v16, v16, v16 quad_perm:[1,0,3,2] row_mask:0xf bank_mask:0xf bound_ctrl:1
	s_nop 1
	v_add_f32_dpp v16, v16, v16 quad_perm:[2,3,0,1] row_mask:0xf bank_mask:0xf bound_ctrl:1
	s_nop 1
	v_mov_b32_dpp v24, v16 row_half_mirror row_mask:0xf bank_mask:0xf bound_ctrl:1
	s_and_saveexec_b64 s[38:39], s[36:37]
	s_cbranch_execz .LBB0_533
	v_add_f32_e32 v16, v16, v24
	v_fmamk_f32 v16, v16, 0x3c800000, v57
	v_mul_f32_e32 v24, 0x4b800000, v16
	v_cmp_gt_f32_e32 vcc, s69, v16
	s_nop 1
	v_cndmask_b32_e32 v16, v16, v24, vcc
	v_rsq_f32_e32 v16, v16
	s_nop 0
	v_mul_f32_e32 v24, 0x45800000, v16
	v_cndmask_b32_e32 v16, v16, v24, vcc
	v_pk_mul_f32 v[24:25], v[16:17], v[224:225] op_sel_hi:[0,1]
	v_pk_mul_f32 v[26:27], v[16:17], v[226:227] op_sel_hi:[0,1]
	v_pk_mul_f32 v[34:35], v[16:17], v[228:229] op_sel_hi:[0,1]
	v_pk_mul_f32 v[36:37], v[16:17], v[230:231] op_sel_hi:[0,1]
	v_pk_mul_f32 v[4:5], v[4:5], v[24:25]
	v_pk_mul_f32 v[6:7], v[6:7], v[26:27]
	v_pk_mul_f32 v[0:1], v[0:1], v[34:35]
	v_pk_mul_f32 v[2:3], v[2:3], v[36:37]

; #define LAS __attribute__((address_space(3)))
; __device__ __forceinline__ void attn_items(const Params& p, LAS unsigned char* lds, int ai0, int aistride) {
;     ...
;                 const size_t qrow = (size_t)(row0 + tok0 + fr);
;                 bf16x8 Qf[2];
;                 {
;                     const bf16x8 r0 = *(const bf16x8*)(Z + qrow * NZ + ZC_AQ + hh * 64 + 8 * fq), r1 = *(const bf16x8*)(Z + qrow * NZ + ZC_AQ + hh * 64 + 32 + 8 * fq);
;                     float q0[8], q1[8]; float ss = 0.f;
; #pragma unroll
;                     for (int e = 0; e < 8; ++e) { q0[e] = bf2f(r0[e]); q1[e] = bf2f(r1[e]); ss += q0[e] * q0[e] + q1[e] * q1[e]; }
;                     ss += __shfl_xor(ss, 16); ss += __shfl_xor(ss, 32);
;                     const float rq = rsqrtf(ss * (1.0f / 64.0f) + 1e-6f) * 0.125f;
;                     const float4 na = *(const float4*)(p.in[9] + 8 * fq), nb = *(const float4*)(p.in[9] + 8 * fq + 4), nc = *(const float4*)(p.in[9] + 32 + 8 * fq), nd = *(const float4*)(p.in[9] + 32 + 8 * fq + 4);
;                     u32x4 w0, w1;
;                     w0.x = cvt_pk_bf16(q0[0] * rq * na.x, q0[1] * rq * na.y); w0.y = cvt_pk_bf16(q0[2] * rq * na.z, q0[3] * rq * na.w);
;                     w0.z = cvt_pk_bf16(q0[4] * rq * nb.x, q0[5] * rq * nb.y); w0.w = cvt_pk_bf16(q0[6] * rq * nb.z, q0[7] * rq * nb.w);
;                     w1.x = cvt_pk_bf16(q1[0] * rq * nc.x, q1[1] * rq * nc.y); w1.y = cvt_pk_bf16(q1[2] * rq * nc.z, q1[3] * rq * nc.w);
;                     w1.z = cvt_pk_bf16(q1[4] * rq * nd.x, q1[5] * rq * nd.y); w1.w = cvt_pk_bf16(q1[6] * rq * nd.z, q1[7] * rq * nd.w);
;                     Qf[0] = __builtin_bit_cast(bf16x8, w0); Qf[1] = __builtin_bit_cast(bf16x8, w1);
;                 }
;                 const float slope = exp2f(-(float)(hh + 1));
;                 const float sink = p.in[11][hh];
;                 const int qoff = samp ? (tok0 + fr + 128) : ((nkc - 1) * 64 + tok0 + fr);
;                 f32x4 s[12]; float mx = sink;
; #pragma unroll
;                 for (int kt = 0; kt < 12; ++kt) {
;                     if (kt < nkt) {
;                         f32x4 acc = {0.f, 0.f, 0.f, 0.f};
; #pragma unroll
;                         for (int kk = 0; kk < 2; ++kk) { const bf16x8 a = *(const LAS bf16x8*)(K_s + (16 * kt + fr) * 72 + 32 * kk + 8 * fq); acc = mfma16(a, Qf[kk], acc); }
; #pragma unroll
.LBB0_546:
	v_or_b32_e32 v0, s4, v45
	v_cmp_gt_u32_e32 vcc, s76, v0
	s_and_saveexec_b64 s[66:67], vcc
	s_cbranch_execz .LBB0_545
	v_lshrrev_b32_e32 v1, s77, v0
	v_and_b32_e32 v0, s78, v0
	v_lshlrev_b32_e32 v14, 4, v0
	v_add_u32_e32 v28, s79, v1
	v_add_u32_e32 v26, v63, v14
	v_mov_b64_e32 v[0:1], s[14:15]
	v_mad_i64_i32 v[0:1], s[0:1], v26, s68, v[0:1]
	v_lshlrev_b32_e32 v16, 7, v28
	v_lshl_add_u64 v[24:25], v[0:1], 0, v[16:17]
	v_mov_b32_e32 v23, v17
	v_lshl_add_u64 v[4:5], v[24:25], 0, v[22:23]
	global_load_dwordx4 v[0:3], v[4:5], off offset:64
	s_nop 0
	global_load_dwordx4 v[4:7], v[4:5], off
	s_nop 0
	global_load_dwordx4 v[8:11], v[20:21], off offset:144
	global_load_dwordx4 v[30:33], v[20:21], off offset:128
	global_load_dwordx4 v[34:37], v[20:21], off offset:16
	global_load_dwordx4 v[38:41], v[20:21], off
	v_and_b32_e32 v13, 64, v58
	v_xor_b32_e32 v12, 16, v58
	v_add_u32_e32 v13, 64, v13
	v_xor_b32_e32 v15, 32, v58
	v_mov_b32_e32 v29, v17
	v_cmp_lt_i32_e32 vcc, v12, v13
	v_add_u32_e32 v23, 1, v28
	ds_read_b128 v[66:69], v61
	ds_read_b128 v[70:73], v61 offset:64
	ds_read_b128 v[74:77], v61 offset:2304
	ds_read_b128 v[78:81], v61 offset:2368
	v_cndmask_b32_e32 v16, v58, v12, vcc
	v_cmp_lt_i32_e32 vcc, v15, v13
	v_lshl_add_u64 v[12:13], v[28:29], 2, s[74:75]
	v_add_u32_e32 v29, v14, v64
	v_cvt_f32_u32_e32 v14, v23
	global_load_dword v23, v[12:13], off
	v_lshlrev_b32_e32 v27, 2, v16
	v_cndmask_b32_e32 v15, v58, v15, vcc
	v_lshlrev_b32_e32 v16, 2, v15
	v_cmp_lt_f32_e64 s[4:5], s70, v14
	v_sub_u32_e32 v15, v29, v18
	v_lshlrev_b32_e32 v238, 1, v18
	v_mov_b32_e32 v239, 0
	v_lshl_add_u64 v[238:239], v[24:25], 0, v[238:239]
	global_load_dwordx2 v[232:233], v[238:239], off offset:1536
	global_load_dwordx2 v[234:235], v[238:239], off offset:1568
	global_load_dwordx2 v[236:237], v[238:239], off offset:1600
	global_load_dwordx2 v[238:239], v[238:239], off offset:1632
	s_waitcnt vmcnt(0)
	v_and_b32_e32 v43, 0xffff0000, v1
	v_lshlrev_b32_e32 v42, 16, v1
	v_and_b32_e32 v1, 0xffff0000, v0
	v_lshlrev_b32_e32 v0, 16, v0
	v_and_b32_e32 v85, 0xffff0000, v5
	v_lshlrev_b32_e32 v84, 16, v5
	v_and_b32_e32 v5, 0xffff0000, v4
	v_lshlrev_b32_e32 v4, 16, v4
	v_pk_mul_f32 v[92:93], v[0:1], v[0:1]
	v_pk_mul_f32 v[90:91], v[42:43], v[42:43]
	v_pk_fma_f32 v[92:93], v[4:5], v[4:5], v[92:93]
	v_and_b32_e32 v13, 0xffff0000, v3
	v_lshlrev_b32_e32 v12, 16, v3
	v_and_b32_e32 v3, 0xffff0000, v2
	v_lshlrev_b32_e32 v2, 16, v2
	v_pk_fma_f32 v[90:91], v[84:85], v[84:85], v[90:91]
	v_add_f32_e32 v65, v92, v93
	v_and_b32_e32 v83, 0xffff0000, v7
	v_lshlrev_b32_e32 v82, 16, v7
	v_and_b32_e32 v7, 0xffff0000, v6
	v_lshlrev_b32_e32 v6, 16, v6
	v_pk_mul_f32 v[88:89], v[2:3], v[2:3]
	v_add_f32_e32 v65, v90, v65
	v_pk_fma_f32 v[88:89], v[6:7], v[6:7], v[88:89]
	v_add_f32_e32 v65, v91, v65
	v_pk_mul_f32 v[86:87], v[12:13], v[12:13]
	v_add_f32_e32 v65, v88, v65
	v_pk_fma_f32 v[86:87], v[82:83], v[82:83], v[86:87]
	v_add_f32_e32 v65, v89, v65
	v_add_f32_e32 v65, v86, v65
	v_add_f32_e32 v65, v87, v65
	ds_bpermute_b32 v86, v27, v65
	v_add_u32_e32 v87, v29, v46
	v_cvt_f32_i32_e32 v90, v87
	v_add_u32_e32 v87, -2, v15
	v_cvt_f32_i32_e32 v92, v87
	s_waitcnt lgkmcnt(0)
	v_add_f32_e32 v65, v65, v86
	ds_bpermute_b32 v86, v16, v65
	v_add_u32_e32 v91, -3, v15
	v_cvt_f32_i32_e32 v89, v15
	v_sub_u32_e32 v88, v29, v47
	v_cvt_f32_i32_e32 v88, v88
	s_waitcnt lgkmcnt(0)
; #define LAS __attribute__((address_space(3)))
; __device__ __forceinline__ unsigned cvt_pk_bf16(float lo, float hi) { const f32v2_t v = {lo, hi}; const bf16v2_t r = __builtin_convertvector(v, bf16v2_t); return __builtin_bit_cast(unsigned, r); }
; __device__ __forceinline__ void attn_items(const Params& p, LAS unsigned char* lds, int ai0, int aistride) {
;     ...
;                     const float rq = rsqrtf(ss * (1.0f / 64.0f) + 1e-6f) * 0.125f;
;                     const float4 na = *(const float4*)(p.in[9] + 8 * fq), nb = *(const float4*)(p.in[9] + 8 * fq + 4), nc = *(const float4*)(p.in[9] + 32 + 8 * fq), nd = *(const float4*)(p.in[9] + 32 + 8 * fq + 4);
;                     u32x4 w0, w1;
;                     w0.x = cvt_pk_bf16(q0[0] * rq * na.x, q0[1] * rq * na.y); w0.y = cvt_pk_bf16(q0[2] * rq * na.z, q0[3] * rq * na.w);
;                     w0.z = cvt_pk_bf16(q0[4] * rq * nb.x, q0[5] * rq * nb.y); w0.w = cvt_pk_bf16(q0[6] * rq * nb.z, q0[7] * rq * nb.w);
;                     w1.x = cvt_pk_bf16(q1[0] * rq * nc.x, q1[1] * rq * nc.y); w1.y = cvt_pk_bf16(q1[2] * rq * nc.z, q1[3] * rq * nc.w);
;                     w1.z = cvt_pk_bf16(q1[4] * rq * nd.x, q1[5] * rq * nd.y); w1.w = cvt_pk_bf16(q1[6] * rq * nd.z, q1[7] * rq * nd.w);
;                     Qf[0] = __builtin_bit_cast(bf16x8, w0); Qf[1] = __builtin_bit_cast(bf16x8, w1);
;                 }
;                 const float slope = exp2f(-(float)(hh + 1));
;                 const float sink = p.in[11][hh];
;                 const int qoff = samp ? (tok0 + fr + 128) : ((nkc - 1) * 64 + tok0 + fr);
;                 f32x4 s[12]; float mx = sink;
; #pragma unroll
;                 for (int kt = 0; kt < 12; ++kt) {
;                     if (kt < nkt) {
;                         f32x4 acc = {0.f, 0.f, 0.f, 0.f};
; #pragma unroll
;                         for (int kk = 0; kk < 2; ++kk) { const bf16x8 a = *(const LAS bf16x8*)(K_s + (16 * kt + fr) * 72 + 32 * kk + 8 * fq); acc = mfma16(a, Qf[kk], acc); }
; #pragma unroll
;                         for (int jj = 0; jj < 4; ++jj) { const int key = 16 * kt + 4 * fq + jj; const bool valid = !samp || key < 144;
;                             const float sv = valid ? acc[jj] - slope * fabsf((float)(qoff - key)) : -1e30f; s[kt][jj] = sv; mx = fmaxf(mx, sv); }
	v_add_f32_e32 v65, v65, v86
	v_fmamk_f32 v65, v65, 0x3c800000, v57
	v_mul_f32_e32 v86, 0x4b800000, v65
	v_cmp_gt_f32_e32 vcc, s69, v65
	s_nop 1
	v_cndmask_b32_e32 v65, v65, v86, vcc
	v_rsq_f32_e32 v65, v65
	v_cndmask_b32_e64 v86, 0, v59, s[4:5]
	v_sub_f32_e32 v14, v86, v14
	v_exp_f32_e32 v93, v14
	v_mul_f32_e32 v14, 0x45800000, v65
	v_cndmask_b32_e32 v14, v65, v14, vcc
	v_mul_f32_e32 v14, 0x3e000000, v14
	v_pk_mul_f32 v[4:5], v[14:15], v[4:5] op_sel_hi:[0,1]
	v_pk_mul_f32 v[84:85], v[14:15], v[84:85] op_sel_hi:[0,1]
	v_pk_mul_f32 v[6:7], v[14:15], v[6:7] op_sel_hi:[0,1]
	v_pk_mul_f32 v[82:83], v[14:15], v[82:83] op_sel_hi:[0,1]
	v_pk_mul_f32 v[0:1], v[14:15], v[0:1] op_sel_hi:[0,1]
	v_pk_mul_f32 v[86:87], v[14:15], v[2:3] op_sel_hi:[0,1]
	v_pk_mul_f32 v[2:3], v[38:39], v[4:5]
	v_pk_mul_f32 v[4:5], v[40:41], v[84:85]
	v_pk_mul_f32 v[6:7], v[34:35], v[6:7]
	v_pk_mul_f32 v[34:35], v[36:37], v[82:83]
	v_pk_mul_f32 v[42:43], v[14:15], v[42:43] op_sel_hi:[0,1]
	v_pk_mul_f32 v[36:37], v[30:31], v[0:1]
	v_cvt_pk_bf16_f32 v0, v2, v3
	v_cvt_pk_bf16_f32 v1, v4, v5
	v_cvt_pk_bf16_f32 v2, v6, v7
	v_cvt_pk_bf16_f32 v3, v34, v35
	v_pk_mul_f32 v[38:39], v[32:33], v[42:43]
	v_pk_mul_f32 v[12:13], v[14:15], v[12:13] op_sel_hi:[0,1]
	v_mfma_f32_16x16x32_bf16 v[30:33], v[66:69], v[0:3], 0
	v_mul_f32_e64 v6, v8, v86
	v_mul_f32_e64 v7, v9, v87
	v_pk_mul_f32 v[12:13], v[10:11], v[12:13]
	v_cvt_pk_bf16_f32 v4, v36, v37
	v_cvt_pk_bf16_f32 v5, v38, v39
	v_cvt_pk_bf16_f32 v6, v6, v7
	v_cvt_pk_bf16_f32 v7, v12, v13
	v_mfma_f32_16x16x32_bf16 v[8:11], v[74:77], v[0:3], 0
	v_cvt_f32_i32_e32 v12, v91
	v_cndmask_b32_e64 v13, 0, v60, s[4:5]
	v_ldexp_f32 v14, v93, v13
	v_mfma_f32_16x16x32_bf16 v[30:33], v[70:73], v[4:7], v[30:33]
	v_subrev_u32_e32 v34, 19, v15
	v_subrev_u32_e32 v13, 18, v15
	v_cvt_f32_i32_e32 v38, v34
	v_mfma_f32_16x16x32_bf16 v[8:11], v[78:81], v[4:7], v[8:11]
	ds_read_b128 v[34:37], v61 offset:4672
	s_nop 2
	v_fma_f32 v78, -v14, |v89|, v30
	v_fma_f32 v74, -v14, |v90|, v31
	v_fma_f32 v70, -v14, |v92|, v32
	v_fma_f32 v69, -v14, |v12|, v33
	ds_read_b128 v[30:33], v61 offset:4608
	v_subrev_u32_e32 v12, 17, v15
	v_cvt_f32_i32_e32 v12, v12
	v_cvt_f32_i32_e32 v13, v13
	v_fma_f32 v66, -v14, |v88|, v8
	v_max3_f32 v8, v23, v78, v74
	v_max3_f32 v8, v8, v70, v69
	v_fma_f32 v71, -v14, |v12|, v9
	v_max3_f32 v12, v8, v66, v71
	v_fma_f32 v67, -v14, |v13|, v10
	v_fma_f32 v65, -v14, |v38|, v11
	s_waitcnt lgkmcnt(0)
	v_mfma_f32_16x16x32_bf16 v[8:11], v[30:33], v[0:3], 0
	v_sub_u32_e32 v13, v29, v48
	v_cvt_f32_i32_e32 v13, v13
	ds_read_b128 v[30:33], v61 offset:6912
	v_mfma_f32_16x16x32_bf16 v[8:11], v[34:37], v[4:7], v[8:11]
	v_subrev_u32_e32 v34, 35, v15
	v_cvt_f32_i32_e32 v38, v34
	ds_read_b128 v[34:37], v61 offset:6976
	v_max3_f32 v12, v12, v67, v65
	s_andn2_b64 vcc, exec, s[26:27]
	s_nop 2
	v_fma_f32 v68, -v14, |v13|, v8
	v_subrev_u32_e32 v8, 33, v15
	v_subrev_u32_e32 v13, 34, v15
	v_cvt_f32_i32_e32 v8, v8
	v_cvt_f32_i32_e32 v13, v13
	v_fma_f32 v72, -v14, |v38|, v11
	v_fma_f32 v79, -v14, |v8|, v9
	v_fma_f32 v75, -v14, |v13|, v10
	s_waitcnt lgkmcnt(1)
	v_mfma_f32_16x16x32_bf16 v[8:11], v[30:33], v[0:3], 0
	v_sub_u32_e32 v13, v29, v49
	v_cvt_f32_i32_e32 v13, v13
	v_subrev_u32_e32 v29, 51, v15
	s_waitcnt lgkmcnt(0)
	v_mfma_f32_16x16x32_bf16 v[8:11], v[34:37], v[4:7], v[8:11]
	v_cvt_f32_i32_e32 v29, v29
	v_max3_f32 v12, v12, v68, v79
	v_max3_f32 v12, v12, v75, v72
	s_nop 4
	v_fma_f32 v76, -v14, |v13|, v8
	v_subrev_u32_e32 v8, 49, v15
	v_cvt_f32_i32_e32 v8, v8
	v_subrev_u32_e32 v13, 50, v15
	v_cvt_f32_i32_e32 v13, v13
	v_fma_f32 v73, -v14, |v29|, v11
	v_fma_f32 v80, -v14, |v8|, v9
	v_max3_f32 v8, v12, v76, v80
	v_fma_f32 v77, -v14, |v13|, v10
	v_max3_f32 v29, v8, v77, v73
	v_cndmask_b32_e64 v8, 0, 1, s[26:27]
	v_cmp_ne_u32_e64 s[4:5], 1, v8
	v_mov_b32_e32 v8, 0xf149f2ca
	s_cbranch_vccnz .LBB0_550
	ds_read_b128 v[10:13], v61 offset:9216
	ds_read_b128 v[30:33], v61 offset:9280
	v_add_u32_e32 v9, 0xffffffbf, v15
	v_subrev_u32_e32 v34, 64, v15
	v_add_u32_e32 v35, 0xffffffbd, v15
	s_waitcnt lgkmcnt(1)
	v_mfma_f32_16x16x32_bf16 v[10:13], v[10:13], v[0:3], 0
	v_add_u32_e32 v36, 0xffffffbe, v15
	v_cvt_f32_i32_e32 v9, v9
	v_cvt_f32_i32_e32 v34, v34
	v_cvt_f32_i32_e32 v36, v36
	v_cvt_f32_i32_e32 v37, v35
	s_waitcnt lgkmcnt(0)
	v_mfma_f32_16x16x32_bf16 v[30:33], v[30:33], v[4:7], v[10:13]
	v_and_b32_e32 v35, 0x7fffffff, v9
	v_and_b32_e32 v34, 0x7fffffff, v34
	s_nop 0
	v_and_b32_e32 v11, 0x7fffffff, v37
	v_and_b32_e32 v10, 0x7fffffff, v36
	s_nop 2
	v_pk_fma_f32 v[12:13], v[14:15], v[34:35], v[30:31] op_sel_hi:[0,1,1] neg_lo:[1,0,0] neg_hi:[1,0,0]
	v_max3_f32 v9, v29, v12, v13
	v_pk_fma_f32 v[10:11], v[14:15], v[10:11], v[32:33] op_sel_hi:[0,1,1] neg_lo:[1,0,0] neg_hi:[1,0,0]
	v_max3_f32 v29, v9, v10, v11
	s_andn2_b64 vcc, exec, s[28:29]
	s_cbranch_vccz .LBB0_551
